# v56 + hand-written MLP-up epilogue (P4,P9): saddr stores, in-place bf16 packing, ~25% fewer VALU
# speedup vs baseline: 1.0059x; 1.0037x over previous
.LBB0_639:
	v_lshl_add_u32 v249, s28, 8, v156
	v_lshl_or_b32 v251, s33, 8, v158
	v_lshlrev_b32_e32 v249, 13, v249
	v_lshl_add_u32 v249, v251, 1, v249
	s_andn2_b64 vcc, exec, s[2:3]
	s_mov_b64 s[0:1], -1
	v_fmamk_f32 v254, v247, 0x3a800000, v164
	v_fmamk_f32 v252, v246, 0x3a800000, v164
	v_fmamk_f32 v250, v245, 0x3a800000, v164
	v_fmamk_f32 v248, v244, 0x3a800000, v164
	v_fmamk_f32 v246, v243, 0x3a800000, v164
	v_fmamk_f32 v244, v242, 0x3a800000, v164
	v_fmamk_f32 v242, v241, 0x3a800000, v164
	v_fmamk_f32 v240, v240, 0x3a800000, v164
	v_rsq_f32_e32 v254, v254
	v_rsq_f32_e32 v252, v252
	v_rsq_f32_e32 v250, v250
	v_rsq_f32_e32 v248, v248
	v_rsq_f32_e32 v246, v246
	v_rsq_f32_e32 v244, v244
	v_rsq_f32_e32 v242, v242
	v_rsq_f32_e32 v240, v240
	s_nop 1
	v_pk_mul_f32 v[124:125], v[124:125], v[240:241] op_sel_hi:[1,0]
	v_pk_mul_f32 v[126:127], v[126:127], v[240:241] op_sel_hi:[1,0]
	v_pk_mul_f32 v[120:121], v[120:121], v[240:241] op_sel_hi:[1,0]
	v_pk_mul_f32 v[122:123], v[122:123], v[240:241] op_sel_hi:[1,0]
	v_pk_mul_f32 v[112:113], v[112:113], v[240:241] op_sel_hi:[1,0]
	v_pk_mul_f32 v[114:115], v[114:115], v[240:241] op_sel_hi:[1,0]
	v_pk_mul_f32 v[108:109], v[108:109], v[240:241] op_sel_hi:[1,0]
	v_pk_mul_f32 v[110:111], v[110:111], v[240:241] op_sel_hi:[1,0]
	v_max_f32_e32 v124, 0, v124
	v_max_f32_e32 v125, 0, v125
	v_max_f32_e32 v126, 0, v126
	v_max_f32_e32 v127, 0, v127
	v_max_f32_e32 v120, 0, v120
	v_max_f32_e32 v121, 0, v121
	v_max_f32_e32 v122, 0, v122
	v_max_f32_e32 v123, 0, v123
	v_max_f32_e32 v112, 0, v112
	v_max_f32_e32 v113, 0, v113
	v_max_f32_e32 v114, 0, v114
	v_max_f32_e32 v115, 0, v115
	v_max_f32_e32 v108, 0, v108
	v_max_f32_e32 v109, 0, v109
	v_max_f32_e32 v110, 0, v110
	v_max_f32_e32 v111, 0, v111
	v_pk_mul_f32 v[124:125], v[124:125], v[124:125]
	v_pk_mul_f32 v[126:127], v[126:127], v[126:127]
	v_pk_mul_f32 v[120:121], v[120:121], v[120:121]
	v_pk_mul_f32 v[122:123], v[122:123], v[122:123]
	v_pk_mul_f32 v[112:113], v[112:113], v[112:113]
	v_pk_mul_f32 v[114:115], v[114:115], v[114:115]
	v_pk_mul_f32 v[108:109], v[108:109], v[108:109]
	v_pk_mul_f32 v[110:111], v[110:111], v[110:111]
	v_cvt_pk_bf16_f32 v124, v124, v125
	v_cvt_pk_bf16_f32 v125, v126, v127
	v_cvt_pk_bf16_f32 v126, v120, v121
	v_cvt_pk_bf16_f32 v127, v122, v123
	v_cvt_pk_bf16_f32 v112, v112, v113
	v_cvt_pk_bf16_f32 v113, v114, v115
	v_cvt_pk_bf16_f32 v114, v108, v109
	v_cvt_pk_bf16_f32 v115, v110, v111
	s_mov_b64 s[98:99], s[92:93]
	global_store_dwordx4 v249, v[124:127], s[98:99]
	global_store_dwordx4 v249, v[112:115], s[98:99] offset:256
	v_pk_mul_f32 v[116:117], v[116:117], v[242:243] op_sel_hi:[1,0]
	v_pk_mul_f32 v[118:119], v[118:119], v[242:243] op_sel_hi:[1,0]
	v_pk_mul_f32 v[104:105], v[104:105], v[242:243] op_sel_hi:[1,0]
	v_pk_mul_f32 v[106:107], v[106:107], v[242:243] op_sel_hi:[1,0]
	v_pk_mul_f32 v[100:101], v[100:101], v[242:243] op_sel_hi:[1,0]
	v_pk_mul_f32 v[102:103], v[102:103], v[242:243] op_sel_hi:[1,0]
	v_pk_mul_f32 v[96:97], v[96:97], v[242:243] op_sel_hi:[1,0]
	v_pk_mul_f32 v[98:99], v[98:99], v[242:243] op_sel_hi:[1,0]
	v_max_f32_e32 v116, 0, v116
	v_max_f32_e32 v117, 0, v117
	v_max_f32_e32 v118, 0, v118
	v_max_f32_e32 v119, 0, v119
	v_max_f32_e32 v104, 0, v104
	v_max_f32_e32 v105, 0, v105
	v_max_f32_e32 v106, 0, v106
	v_max_f32_e32 v107, 0, v107
	v_max_f32_e32 v100, 0, v100
	v_max_f32_e32 v101, 0, v101
	v_max_f32_e32 v102, 0, v102
	v_max_f32_e32 v103, 0, v103
	v_max_f32_e32 v96, 0, v96
	v_max_f32_e32 v97, 0, v97
	v_max_f32_e32 v98, 0, v98
	v_max_f32_e32 v99, 0, v99
	v_pk_mul_f32 v[116:117], v[116:117], v[116:117]
	v_pk_mul_f32 v[118:119], v[118:119], v[118:119]
	v_pk_mul_f32 v[104:105], v[104:105], v[104:105]
	v_pk_mul_f32 v[106:107], v[106:107], v[106:107]
	v_pk_mul_f32 v[100:101], v[100:101], v[100:101]
	v_pk_mul_f32 v[102:103], v[102:103], v[102:103]
	v_pk_mul_f32 v[96:97], v[96:97], v[96:97]
	v_pk_mul_f32 v[98:99], v[98:99], v[98:99]
	v_cvt_pk_bf16_f32 v116, v116, v117
	v_cvt_pk_bf16_f32 v117, v118, v119
	v_cvt_pk_bf16_f32 v118, v104, v105
	v_cvt_pk_bf16_f32 v119, v106, v107
	v_cvt_pk_bf16_f32 v100, v100, v101
	v_cvt_pk_bf16_f32 v101, v102, v103
	v_cvt_pk_bf16_f32 v102, v96, v97
	v_cvt_pk_bf16_f32 v103, v98, v99
	s_add_u32 s98, s92, 0x20000
	s_addc_u32 s99, s93, 0
	global_store_dwordx4 v249, v[116:119], s[98:99]
	global_store_dwordx4 v249, v[100:103], s[98:99] offset:256
	v_pk_mul_f32 v[92:93], v[92:93], v[244:245] op_sel_hi:[1,0]
	v_pk_mul_f32 v[94:95], v[94:95], v[244:245] op_sel_hi:[1,0]
	v_pk_mul_f32 v[88:89], v[88:89], v[244:245] op_sel_hi:[1,0]
	v_pk_mul_f32 v[90:91], v[90:91], v[244:245] op_sel_hi:[1,0]
	v_pk_mul_f32 v[84:85], v[84:85], v[244:245] op_sel_hi:[1,0]
	v_pk_mul_f32 v[86:87], v[86:87], v[244:245] op_sel_hi:[1,0]
	v_pk_mul_f32 v[80:81], v[80:81], v[244:245] op_sel_hi:[1,0]
	v_pk_mul_f32 v[82:83], v[82:83], v[244:245] op_sel_hi:[1,0]
	v_max_f32_e32 v92, 0, v92
	v_max_f32_e32 v93, 0, v93
	v_max_f32_e32 v94, 0, v94
	v_max_f32_e32 v95, 0, v95
	v_max_f32_e32 v88, 0, v88
	v_max_f32_e32 v89, 0, v89
	v_max_f32_e32 v90, 0, v90
	v_max_f32_e32 v91, 0, v91
	v_max_f32_e32 v84, 0, v84
	v_max_f32_e32 v85, 0, v85
	v_max_f32_e32 v86, 0, v86
	v_max_f32_e32 v87, 0, v87
	v_max_f32_e32 v80, 0, v80
	v_max_f32_e32 v81, 0, v81
	v_max_f32_e32 v82, 0, v82
	v_max_f32_e32 v83, 0, v83
	v_pk_mul_f32 v[92:93], v[92:93], v[92:93]
	v_pk_mul_f32 v[94:95], v[94:95], v[94:95]
	v_pk_mul_f32 v[88:89], v[88:89], v[88:89]
	v_pk_mul_f32 v[90:91], v[90:91], v[90:91]
	v_pk_mul_f32 v[84:85], v[84:85], v[84:85]
	v_pk_mul_f32 v[86:87], v[86:87], v[86:87]
	v_pk_mul_f32 v[80:81], v[80:81], v[80:81]
	v_pk_mul_f32 v[82:83], v[82:83], v[82:83]
	v_cvt_pk_bf16_f32 v92, v92, v93
	v_cvt_pk_bf16_f32 v93, v94, v95
	v_cvt_pk_bf16_f32 v94, v88, v89
	v_cvt_pk_bf16_f32 v95, v90, v91
	v_cvt_pk_bf16_f32 v84, v84, v85
	v_cvt_pk_bf16_f32 v85, v86, v87
	v_cvt_pk_bf16_f32 v86, v80, v81
	v_cvt_pk_bf16_f32 v87, v82, v83
	s_add_u32 s98, s92, 0x40000
	s_addc_u32 s99, s93, 0
	global_store_dwordx4 v249, v[92:95], s[98:99]
	global_store_dwordx4 v249, v[84:87], s[98:99] offset:256
	v_pk_mul_f32 v[76:77], v[76:77], v[246:247] op_sel_hi:[1,0]
	v_pk_mul_f32 v[78:79], v[78:79], v[246:247] op_sel_hi:[1,0]
	v_pk_mul_f32 v[72:73], v[72:73], v[246:247] op_sel_hi:[1,0]
	v_pk_mul_f32 v[74:75], v[74:75], v[246:247] op_sel_hi:[1,0]
	v_pk_mul_f32 v[68:69], v[68:69], v[246:247] op_sel_hi:[1,0]
	v_pk_mul_f32 v[70:71], v[70:71], v[246:247] op_sel_hi:[1,0]
	v_pk_mul_f32 v[64:65], v[64:65], v[246:247] op_sel_hi:[1,0]
	v_pk_mul_f32 v[66:67], v[66:67], v[246:247] op_sel_hi:[1,0]
	v_max_f32_e32 v76, 0, v76
	v_max_f32_e32 v77, 0, v77
	v_max_f32_e32 v78, 0, v78
	v_max_f32_e32 v79, 0, v79
	v_max_f32_e32 v72, 0, v72
	v_max_f32_e32 v73, 0, v73
	v_max_f32_e32 v74, 0, v74
	v_max_f32_e32 v75, 0, v75
	v_max_f32_e32 v68, 0, v68
	v_max_f32_e32 v69, 0, v69
	v_max_f32_e32 v70, 0, v70
	v_max_f32_e32 v71, 0, v71
	v_max_f32_e32 v64, 0, v64
	v_max_f32_e32 v65, 0, v65
	v_max_f32_e32 v66, 0, v66
	v_max_f32_e32 v67, 0, v67
	v_pk_mul_f32 v[76:77], v[76:77], v[76:77]
	v_pk_mul_f32 v[78:79], v[78:79], v[78:79]
	v_pk_mul_f32 v[72:73], v[72:73], v[72:73]
	v_pk_mul_f32 v[74:75], v[74:75], v[74:75]
	v_pk_mul_f32 v[68:69], v[68:69], v[68:69]
	v_pk_mul_f32 v[70:71], v[70:71], v[70:71]
	v_pk_mul_f32 v[64:65], v[64:65], v[64:65]
	v_pk_mul_f32 v[66:67], v[66:67], v[66:67]
	v_cvt_pk_bf16_f32 v76, v76, v77
	v_cvt_pk_bf16_f32 v77, v78, v79
	v_cvt_pk_bf16_f32 v78, v72, v73
	v_cvt_pk_bf16_f32 v79, v74, v75
	v_cvt_pk_bf16_f32 v68, v68, v69
	v_cvt_pk_bf16_f32 v69, v70, v71
	v_cvt_pk_bf16_f32 v70, v64, v65
	v_cvt_pk_bf16_f32 v71, v66, v67
	s_add_u32 s98, s92, 0x60000
	s_addc_u32 s99, s93, 0
	global_store_dwordx4 v249, v[76:79], s[98:99]
	global_store_dwordx4 v249, v[68:71], s[98:99] offset:256
	v_pk_mul_f32 v[60:61], v[60:61], v[248:249] op_sel_hi:[1,0]
	v_pk_mul_f32 v[62:63], v[62:63], v[248:249] op_sel_hi:[1,0]
	v_pk_mul_f32 v[56:57], v[56:57], v[248:249] op_sel_hi:[1,0]
	v_pk_mul_f32 v[58:59], v[58:59], v[248:249] op_sel_hi:[1,0]
	v_pk_mul_f32 v[52:53], v[52:53], v[248:249] op_sel_hi:[1,0]
	v_pk_mul_f32 v[54:55], v[54:55], v[248:249] op_sel_hi:[1,0]
	v_pk_mul_f32 v[48:49], v[48:49], v[248:249] op_sel_hi:[1,0]
	v_pk_mul_f32 v[50:51], v[50:51], v[248:249] op_sel_hi:[1,0]
	v_max_f32_e32 v60, 0, v60
	v_max_f32_e32 v61, 0, v61
	v_max_f32_e32 v62, 0, v62
	v_max_f32_e32 v63, 0, v63
	v_max_f32_e32 v56, 0, v56
	v_max_f32_e32 v57, 0, v57
	v_max_f32_e32 v58, 0, v58
	v_max_f32_e32 v59, 0, v59
	v_max_f32_e32 v52, 0, v52
	v_max_f32_e32 v53, 0, v53
	v_max_f32_e32 v54, 0, v54
	v_max_f32_e32 v55, 0, v55
	v_max_f32_e32 v48, 0, v48
	v_max_f32_e32 v49, 0, v49
	v_max_f32_e32 v50, 0, v50
	v_max_f32_e32 v51, 0, v51
	v_pk_mul_f32 v[60:61], v[60:61], v[60:61]
	v_pk_mul_f32 v[62:63], v[62:63], v[62:63]
	v_pk_mul_f32 v[56:57], v[56:57], v[56:57]
	v_pk_mul_f32 v[58:59], v[58:59], v[58:59]
	v_pk_mul_f32 v[52:53], v[52:53], v[52:53]
	v_pk_mul_f32 v[54:55], v[54:55], v[54:55]
	v_pk_mul_f32 v[48:49], v[48:49], v[48:49]
	v_pk_mul_f32 v[50:51], v[50:51], v[50:51]
	v_cvt_pk_bf16_f32 v60, v60, v61
	v_cvt_pk_bf16_f32 v61, v62, v63
	v_cvt_pk_bf16_f32 v62, v56, v57
	v_cvt_pk_bf16_f32 v63, v58, v59
	v_cvt_pk_bf16_f32 v52, v52, v53
	v_cvt_pk_bf16_f32 v53, v54, v55
	v_cvt_pk_bf16_f32 v54, v48, v49
	v_cvt_pk_bf16_f32 v55, v50, v51
	s_add_u32 s98, s92, 0x100000
	s_addc_u32 s99, s93, 0
	global_store_dwordx4 v249, v[60:63], s[98:99]
	global_store_dwordx4 v249, v[52:55], s[98:99] offset:256
	v_pk_mul_f32 v[44:45], v[44:45], v[250:251] op_sel_hi:[1,0]
	v_pk_mul_f32 v[46:47], v[46:47], v[250:251] op_sel_hi:[1,0]
	v_pk_mul_f32 v[40:41], v[40:41], v[250:251] op_sel_hi:[1,0]
	v_pk_mul_f32 v[42:43], v[42:43], v[250:251] op_sel_hi:[1,0]
	v_pk_mul_f32 v[36:37], v[36:37], v[250:251] op_sel_hi:[1,0]
	v_pk_mul_f32 v[38:39], v[38:39], v[250:251] op_sel_hi:[1,0]
	v_pk_mul_f32 v[32:33], v[32:33], v[250:251] op_sel_hi:[1,0]
	v_pk_mul_f32 v[34:35], v[34:35], v[250:251] op_sel_hi:[1,0]
	v_max_f32_e32 v44, 0, v44
	v_max_f32_e32 v45, 0, v45
	v_max_f32_e32 v46, 0, v46
	v_max_f32_e32 v47, 0, v47
	v_max_f32_e32 v40, 0, v40
	v_max_f32_e32 v41, 0, v41
	v_max_f32_e32 v42, 0, v42
	v_max_f32_e32 v43, 0, v43
	v_max_f32_e32 v36, 0, v36
	v_max_f32_e32 v37, 0, v37
	v_max_f32_e32 v38, 0, v38
	v_max_f32_e32 v39, 0, v39
	v_max_f32_e32 v32, 0, v32
	v_max_f32_e32 v33, 0, v33
	v_max_f32_e32 v34, 0, v34
	v_max_f32_e32 v35, 0, v35
	v_pk_mul_f32 v[44:45], v[44:45], v[44:45]
	v_pk_mul_f32 v[46:47], v[46:47], v[46:47]
	v_pk_mul_f32 v[40:41], v[40:41], v[40:41]
	v_pk_mul_f32 v[42:43], v[42:43], v[42:43]
	v_pk_mul_f32 v[36:37], v[36:37], v[36:37]
	v_pk_mul_f32 v[38:39], v[38:39], v[38:39]
	v_pk_mul_f32 v[32:33], v[32:33], v[32:33]
	v_pk_mul_f32 v[34:35], v[34:35], v[34:35]
	v_cvt_pk_bf16_f32 v44, v44, v45
	v_cvt_pk_bf16_f32 v45, v46, v47
	v_cvt_pk_bf16_f32 v46, v40, v41
	v_cvt_pk_bf16_f32 v47, v42, v43
	v_cvt_pk_bf16_f32 v36, v36, v37
	v_cvt_pk_bf16_f32 v37, v38, v39
	v_cvt_pk_bf16_f32 v38, v32, v33
	v_cvt_pk_bf16_f32 v39, v34, v35
	s_add_u32 s98, s92, 0x120000
	s_addc_u32 s99, s93, 0
	global_store_dwordx4 v249, v[44:47], s[98:99]
	global_store_dwordx4 v249, v[36:39], s[98:99] offset:256
	v_pk_mul_f32 v[28:29], v[28:29], v[252:253] op_sel_hi:[1,0]
	v_pk_mul_f32 v[30:31], v[30:31], v[252:253] op_sel_hi:[1,0]
	v_pk_mul_f32 v[24:25], v[24:25], v[252:253] op_sel_hi:[1,0]
	v_pk_mul_f32 v[26:27], v[26:27], v[252:253] op_sel_hi:[1,0]
	v_pk_mul_f32 v[20:21], v[20:21], v[252:253] op_sel_hi:[1,0]
	v_pk_mul_f32 v[22:23], v[22:23], v[252:253] op_sel_hi:[1,0]
	v_pk_mul_f32 v[16:17], v[16:17], v[252:253] op_sel_hi:[1,0]
	v_pk_mul_f32 v[18:19], v[18:19], v[252:253] op_sel_hi:[1,0]
	v_max_f32_e32 v28, 0, v28
	v_max_f32_e32 v29, 0, v29
	v_max_f32_e32 v30, 0, v30
	v_max_f32_e32 v31, 0, v31
	v_max_f32_e32 v24, 0, v24
	v_max_f32_e32 v25, 0, v25
	v_max_f32_e32 v26, 0, v26
	v_max_f32_e32 v27, 0, v27
	v_max_f32_e32 v20, 0, v20
	v_max_f32_e32 v21, 0, v21
	v_max_f32_e32 v22, 0, v22
	v_max_f32_e32 v23, 0, v23
	v_max_f32_e32 v16, 0, v16
	v_max_f32_e32 v17, 0, v17
	v_max_f32_e32 v18, 0, v18
	v_max_f32_e32 v19, 0, v19
	v_pk_mul_f32 v[28:29], v[28:29], v[28:29]
	v_pk_mul_f32 v[30:31], v[30:31], v[30:31]
	v_pk_mul_f32 v[24:25], v[24:25], v[24:25]
	v_pk_mul_f32 v[26:27], v[26:27], v[26:27]
	v_pk_mul_f32 v[20:21], v[20:21], v[20:21]
	v_pk_mul_f32 v[22:23], v[22:23], v[22:23]
	v_pk_mul_f32 v[16:17], v[16:17], v[16:17]
	v_pk_mul_f32 v[18:19], v[18:19], v[18:19]
	v_cvt_pk_bf16_f32 v28, v28, v29
	v_cvt_pk_bf16_f32 v29, v30, v31
	v_cvt_pk_bf16_f32 v30, v24, v25
	v_cvt_pk_bf16_f32 v31, v26, v27
	v_cvt_pk_bf16_f32 v20, v20, v21
	v_cvt_pk_bf16_f32 v21, v22, v23
	v_cvt_pk_bf16_f32 v22, v16, v17
	v_cvt_pk_bf16_f32 v23, v18, v19
	s_add_u32 s98, s92, 0x140000
	s_addc_u32 s99, s93, 0
	global_store_dwordx4 v249, v[28:31], s[98:99]
	global_store_dwordx4 v249, v[20:23], s[98:99] offset:256
	v_pk_mul_f32 v[12:13], v[12:13], v[254:255] op_sel_hi:[1,0]
	v_pk_mul_f32 v[14:15], v[14:15], v[254:255] op_sel_hi:[1,0]
	v_pk_mul_f32 v[8:9], v[8:9], v[254:255] op_sel_hi:[1,0]
	v_pk_mul_f32 v[10:11], v[10:11], v[254:255] op_sel_hi:[1,0]
	v_pk_mul_f32 v[4:5], v[4:5], v[254:255] op_sel_hi:[1,0]
	v_pk_mul_f32 v[6:7], v[6:7], v[254:255] op_sel_hi:[1,0]
	v_pk_mul_f32 v[0:1], v[0:1], v[254:255] op_sel_hi:[1,0]
	v_pk_mul_f32 v[2:3], v[2:3], v[254:255] op_sel_hi:[1,0]
	v_max_f32_e32 v12, 0, v12
	v_max_f32_e32 v13, 0, v13
	v_max_f32_e32 v14, 0, v14
	v_max_f32_e32 v15, 0, v15
	v_max_f32_e32 v8, 0, v8
	v_max_f32_e32 v9, 0, v9
	v_max_f32_e32 v10, 0, v10
	v_max_f32_e32 v11, 0, v11
	v_max_f32_e32 v4, 0, v4
	v_max_f32_e32 v5, 0, v5
	v_max_f32_e32 v6, 0, v6
	v_max_f32_e32 v7, 0, v7
	v_max_f32_e32 v0, 0, v0
	v_max_f32_e32 v1, 0, v1
	v_max_f32_e32 v2, 0, v2
	v_max_f32_e32 v3, 0, v3
	v_pk_mul_f32 v[12:13], v[12:13], v[12:13]
	v_pk_mul_f32 v[14:15], v[14:15], v[14:15]
	v_pk_mul_f32 v[8:9], v[8:9], v[8:9]
	v_pk_mul_f32 v[10:11], v[10:11], v[10:11]
	v_pk_mul_f32 v[4:5], v[4:5], v[4:5]
	v_pk_mul_f32 v[6:7], v[6:7], v[6:7]
	v_pk_mul_f32 v[0:1], v[0:1], v[0:1]
	v_pk_mul_f32 v[2:3], v[2:3], v[2:3]
	v_cvt_pk_bf16_f32 v12, v12, v13
	v_cvt_pk_bf16_f32 v13, v14, v15
	v_cvt_pk_bf16_f32 v14, v8, v9
	v_cvt_pk_bf16_f32 v15, v10, v11
	v_cvt_pk_bf16_f32 v4, v4, v5
	v_cvt_pk_bf16_f32 v5, v6, v7
	v_cvt_pk_bf16_f32 v6, v0, v1
	v_cvt_pk_bf16_f32 v7, v2, v3
	s_add_u32 s98, s92, 0x160000
	s_addc_u32 s99, s93, 0
	global_store_dwordx4 v249, v[12:15], s[98:99]
	global_store_dwordx4 v249, v[4:7], s[98:99] offset:256
	s_cbranch_vccnz .LBB0_632
	s_andn2_b64 vcc, exec, s[4:5]
	s_cbranch_vccnz .LBB0_631
	s_barrier
	s_branch .LBB0_631

.LBB0_1491:
	v_lshl_add_u32 v249, s20, 8, v156
	v_lshl_or_b32 v251, s33, 8, v158
	v_lshlrev_b32_e32 v249, 13, v249
	v_lshl_add_u32 v249, v251, 1, v249
	s_andn2_b64 vcc, exec, s[4:5]
	s_mov_b64 s[0:1], -1
	v_fmamk_f32 v254, v247, 0x3a800000, v164
	v_fmamk_f32 v252, v246, 0x3a800000, v164
	v_fmamk_f32 v250, v245, 0x3a800000, v164
	v_fmamk_f32 v248, v244, 0x3a800000, v164
	v_fmamk_f32 v246, v243, 0x3a800000, v164
	v_fmamk_f32 v244, v242, 0x3a800000, v164
	v_fmamk_f32 v242, v241, 0x3a800000, v164
	v_fmamk_f32 v240, v240, 0x3a800000, v164
	v_rsq_f32_e32 v254, v254
	v_rsq_f32_e32 v252, v252
	v_rsq_f32_e32 v250, v250
	v_rsq_f32_e32 v248, v248
	v_rsq_f32_e32 v246, v246
	v_rsq_f32_e32 v244, v244
	v_rsq_f32_e32 v242, v242
	v_rsq_f32_e32 v240, v240
	s_nop 1
	v_pk_mul_f32 v[124:125], v[124:125], v[240:241] op_sel_hi:[1,0]
	v_pk_mul_f32 v[126:127], v[126:127], v[240:241] op_sel_hi:[1,0]
	v_pk_mul_f32 v[120:121], v[120:121], v[240:241] op_sel_hi:[1,0]
	v_pk_mul_f32 v[122:123], v[122:123], v[240:241] op_sel_hi:[1,0]
	v_pk_mul_f32 v[112:113], v[112:113], v[240:241] op_sel_hi:[1,0]
	v_pk_mul_f32 v[114:115], v[114:115], v[240:241] op_sel_hi:[1,0]
	v_pk_mul_f32 v[108:109], v[108:109], v[240:241] op_sel_hi:[1,0]
	v_pk_mul_f32 v[110:111], v[110:111], v[240:241] op_sel_hi:[1,0]
	v_max_f32_e32 v124, 0, v124
	v_max_f32_e32 v125, 0, v125
	v_max_f32_e32 v126, 0, v126
	v_max_f32_e32 v127, 0, v127
	v_max_f32_e32 v120, 0, v120
	v_max_f32_e32 v121, 0, v121
	v_max_f32_e32 v122, 0, v122
	v_max_f32_e32 v123, 0, v123
	v_max_f32_e32 v112, 0, v112
	v_max_f32_e32 v113, 0, v113
	v_max_f32_e32 v114, 0, v114
	v_max_f32_e32 v115, 0, v115
	v_max_f32_e32 v108, 0, v108
	v_max_f32_e32 v109, 0, v109
	v_max_f32_e32 v110, 0, v110
	v_max_f32_e32 v111, 0, v111
	v_pk_mul_f32 v[124:125], v[124:125], v[124:125]
	v_pk_mul_f32 v[126:127], v[126:127], v[126:127]
	v_pk_mul_f32 v[120:121], v[120:121], v[120:121]
	v_pk_mul_f32 v[122:123], v[122:123], v[122:123]
	v_pk_mul_f32 v[112:113], v[112:113], v[112:113]
	v_pk_mul_f32 v[114:115], v[114:115], v[114:115]
	v_pk_mul_f32 v[108:109], v[108:109], v[108:109]
	v_pk_mul_f32 v[110:111], v[110:111], v[110:111]
	v_cvt_pk_bf16_f32 v124, v124, v125
	v_cvt_pk_bf16_f32 v125, v126, v127
	v_cvt_pk_bf16_f32 v126, v120, v121
	v_cvt_pk_bf16_f32 v127, v122, v123
	v_cvt_pk_bf16_f32 v112, v112, v113
	v_cvt_pk_bf16_f32 v113, v114, v115
	v_cvt_pk_bf16_f32 v114, v108, v109
	v_cvt_pk_bf16_f32 v115, v110, v111
	s_mov_b64 s[98:99], s[68:69]
	global_store_dwordx4 v249, v[124:127], s[98:99]
	global_store_dwordx4 v249, v[112:115], s[98:99] offset:256
	v_pk_mul_f32 v[116:117], v[116:117], v[242:243] op_sel_hi:[1,0]
	v_pk_mul_f32 v[118:119], v[118:119], v[242:243] op_sel_hi:[1,0]
	v_pk_mul_f32 v[104:105], v[104:105], v[242:243] op_sel_hi:[1,0]
	v_pk_mul_f32 v[106:107], v[106:107], v[242:243] op_sel_hi:[1,0]
	v_pk_mul_f32 v[100:101], v[100:101], v[242:243] op_sel_hi:[1,0]
	v_pk_mul_f32 v[102:103], v[102:103], v[242:243] op_sel_hi:[1,0]
	v_pk_mul_f32 v[96:97], v[96:97], v[242:243] op_sel_hi:[1,0]
	v_pk_mul_f32 v[98:99], v[98:99], v[242:243] op_sel_hi:[1,0]
	v_max_f32_e32 v116, 0, v116
	v_max_f32_e32 v117, 0, v117
	v_max_f32_e32 v118, 0, v118
	v_max_f32_e32 v119, 0, v119
	v_max_f32_e32 v104, 0, v104
	v_max_f32_e32 v105, 0, v105
	v_max_f32_e32 v106, 0, v106
	v_max_f32_e32 v107, 0, v107
	v_max_f32_e32 v100, 0, v100
	v_max_f32_e32 v101, 0, v101
	v_max_f32_e32 v102, 0, v102
	v_max_f32_e32 v103, 0, v103
	v_max_f32_e32 v96, 0, v96
	v_max_f32_e32 v97, 0, v97
	v_max_f32_e32 v98, 0, v98
	v_max_f32_e32 v99, 0, v99
	v_pk_mul_f32 v[116:117], v[116:117], v[116:117]
	v_pk_mul_f32 v[118:119], v[118:119], v[118:119]
	v_pk_mul_f32 v[104:105], v[104:105], v[104:105]
	v_pk_mul_f32 v[106:107], v[106:107], v[106:107]
	v_pk_mul_f32 v[100:101], v[100:101], v[100:101]
	v_pk_mul_f32 v[102:103], v[102:103], v[102:103]
	v_pk_mul_f32 v[96:97], v[96:97], v[96:97]
	v_pk_mul_f32 v[98:99], v[98:99], v[98:99]
	v_cvt_pk_bf16_f32 v116, v116, v117
	v_cvt_pk_bf16_f32 v117, v118, v119
	v_cvt_pk_bf16_f32 v118, v104, v105
	v_cvt_pk_bf16_f32 v119, v106, v107
	v_cvt_pk_bf16_f32 v100, v100, v101
	v_cvt_pk_bf16_f32 v101, v102, v103
	v_cvt_pk_bf16_f32 v102, v96, v97
	v_cvt_pk_bf16_f32 v103, v98, v99
	s_add_u32 s98, s68, 0x20000
	s_addc_u32 s99, s69, 0
	global_store_dwordx4 v249, v[116:119], s[98:99]
	global_store_dwordx4 v249, v[100:103], s[98:99] offset:256
	v_pk_mul_f32 v[92:93], v[92:93], v[244:245] op_sel_hi:[1,0]
	v_pk_mul_f32 v[94:95], v[94:95], v[244:245] op_sel_hi:[1,0]
	v_pk_mul_f32 v[88:89], v[88:89], v[244:245] op_sel_hi:[1,0]
	v_pk_mul_f32 v[90:91], v[90:91], v[244:245] op_sel_hi:[1,0]
	v_pk_mul_f32 v[84:85], v[84:85], v[244:245] op_sel_hi:[1,0]
	v_pk_mul_f32 v[86:87], v[86:87], v[244:245] op_sel_hi:[1,0]
	v_pk_mul_f32 v[80:81], v[80:81], v[244:245] op_sel_hi:[1,0]
	v_pk_mul_f32 v[82:83], v[82:83], v[244:245] op_sel_hi:[1,0]
	v_max_f32_e32 v92, 0, v92
	v_max_f32_e32 v93, 0, v93
	v_max_f32_e32 v94, 0, v94
	v_max_f32_e32 v95, 0, v95
	v_max_f32_e32 v88, 0, v88
	v_max_f32_e32 v89, 0, v89
	v_max_f32_e32 v90, 0, v90
	v_max_f32_e32 v91, 0, v91
	v_max_f32_e32 v84, 0, v84
	v_max_f32_e32 v85, 0, v85
	v_max_f32_e32 v86, 0, v86
	v_max_f32_e32 v87, 0, v87
	v_max_f32_e32 v80, 0, v80
	v_max_f32_e32 v81, 0, v81
	v_max_f32_e32 v82, 0, v82
	v_max_f32_e32 v83, 0, v83
	v_pk_mul_f32 v[92:93], v[92:93], v[92:93]
	v_pk_mul_f32 v[94:95], v[94:95], v[94:95]
	v_pk_mul_f32 v[88:89], v[88:89], v[88:89]
	v_pk_mul_f32 v[90:91], v[90:91], v[90:91]
	v_pk_mul_f32 v[84:85], v[84:85], v[84:85]
	v_pk_mul_f32 v[86:87], v[86:87], v[86:87]
	v_pk_mul_f32 v[80:81], v[80:81], v[80:81]
	v_pk_mul_f32 v[82:83], v[82:83], v[82:83]
	v_cvt_pk_bf16_f32 v92, v92, v93
	v_cvt_pk_bf16_f32 v93, v94, v95
	v_cvt_pk_bf16_f32 v94, v88, v89
	v_cvt_pk_bf16_f32 v95, v90, v91
	v_cvt_pk_bf16_f32 v84, v84, v85
	v_cvt_pk_bf16_f32 v85, v86, v87
	v_cvt_pk_bf16_f32 v86, v80, v81
	v_cvt_pk_bf16_f32 v87, v82, v83
	s_add_u32 s98, s68, 0x40000
	s_addc_u32 s99, s69, 0
	global_store_dwordx4 v249, v[92:95], s[98:99]
	global_store_dwordx4 v249, v[84:87], s[98:99] offset:256
	v_pk_mul_f32 v[76:77], v[76:77], v[246:247] op_sel_hi:[1,0]
	v_pk_mul_f32 v[78:79], v[78:79], v[246:247] op_sel_hi:[1,0]
	v_pk_mul_f32 v[72:73], v[72:73], v[246:247] op_sel_hi:[1,0]
	v_pk_mul_f32 v[74:75], v[74:75], v[246:247] op_sel_hi:[1,0]
	v_pk_mul_f32 v[68:69], v[68:69], v[246:247] op_sel_hi:[1,0]
	v_pk_mul_f32 v[70:71], v[70:71], v[246:247] op_sel_hi:[1,0]
	v_pk_mul_f32 v[64:65], v[64:65], v[246:247] op_sel_hi:[1,0]
	v_pk_mul_f32 v[66:67], v[66:67], v[246:247] op_sel_hi:[1,0]
	v_max_f32_e32 v76, 0, v76
	v_max_f32_e32 v77, 0, v77
	v_max_f32_e32 v78, 0, v78
	v_max_f32_e32 v79, 0, v79
	v_max_f32_e32 v72, 0, v72
	v_max_f32_e32 v73, 0, v73
	v_max_f32_e32 v74, 0, v74
	v_max_f32_e32 v75, 0, v75
	v_max_f32_e32 v68, 0, v68
	v_max_f32_e32 v69, 0, v69
	v_max_f32_e32 v70, 0, v70
	v_max_f32_e32 v71, 0, v71
	v_max_f32_e32 v64, 0, v64
	v_max_f32_e32 v65, 0, v65
	v_max_f32_e32 v66, 0, v66
	v_max_f32_e32 v67, 0, v67
	v_pk_mul_f32 v[76:77], v[76:77], v[76:77]
	v_pk_mul_f32 v[78:79], v[78:79], v[78:79]
	v_pk_mul_f32 v[72:73], v[72:73], v[72:73]
	v_pk_mul_f32 v[74:75], v[74:75], v[74:75]
	v_pk_mul_f32 v[68:69], v[68:69], v[68:69]
	v_pk_mul_f32 v[70:71], v[70:71], v[70:71]
	v_pk_mul_f32 v[64:65], v[64:65], v[64:65]
	v_pk_mul_f32 v[66:67], v[66:67], v[66:67]
	v_cvt_pk_bf16_f32 v76, v76, v77
	v_cvt_pk_bf16_f32 v77, v78, v79
	v_cvt_pk_bf16_f32 v78, v72, v73
	v_cvt_pk_bf16_f32 v79, v74, v75
	v_cvt_pk_bf16_f32 v68, v68, v69
	v_cvt_pk_bf16_f32 v69, v70, v71
	v_cvt_pk_bf16_f32 v70, v64, v65
	v_cvt_pk_bf16_f32 v71, v66, v67
	s_add_u32 s98, s68, 0x60000
	s_addc_u32 s99, s69, 0
	global_store_dwordx4 v249, v[76:79], s[98:99]
	global_store_dwordx4 v249, v[68:71], s[98:99] offset:256
	v_pk_mul_f32 v[60:61], v[60:61], v[248:249] op_sel_hi:[1,0]
	v_pk_mul_f32 v[62:63], v[62:63], v[248:249] op_sel_hi:[1,0]
	v_pk_mul_f32 v[56:57], v[56:57], v[248:249] op_sel_hi:[1,0]
	v_pk_mul_f32 v[58:59], v[58:59], v[248:249] op_sel_hi:[1,0]
	v_pk_mul_f32 v[52:53], v[52:53], v[248:249] op_sel_hi:[1,0]
	v_pk_mul_f32 v[54:55], v[54:55], v[248:249] op_sel_hi:[1,0]
	v_pk_mul_f32 v[48:49], v[48:49], v[248:249] op_sel_hi:[1,0]
	v_pk_mul_f32 v[50:51], v[50:51], v[248:249] op_sel_hi:[1,0]
	v_max_f32_e32 v60, 0, v60
	v_max_f32_e32 v61, 0, v61
	v_max_f32_e32 v62, 0, v62
	v_max_f32_e32 v63, 0, v63
	v_max_f32_e32 v56, 0, v56
	v_max_f32_e32 v57, 0, v57
	v_max_f32_e32 v58, 0, v58
	v_max_f32_e32 v59, 0, v59
	v_max_f32_e32 v52, 0, v52
	v_max_f32_e32 v53, 0, v53
	v_max_f32_e32 v54, 0, v54
	v_max_f32_e32 v55, 0, v55
	v_max_f32_e32 v48, 0, v48
	v_max_f32_e32 v49, 0, v49
	v_max_f32_e32 v50, 0, v50
	v_max_f32_e32 v51, 0, v51
	v_pk_mul_f32 v[60:61], v[60:61], v[60:61]
	v_pk_mul_f32 v[62:63], v[62:63], v[62:63]
	v_pk_mul_f32 v[56:57], v[56:57], v[56:57]
	v_pk_mul_f32 v[58:59], v[58:59], v[58:59]
	v_pk_mul_f32 v[52:53], v[52:53], v[52:53]
	v_pk_mul_f32 v[54:55], v[54:55], v[54:55]
	v_pk_mul_f32 v[48:49], v[48:49], v[48:49]
	v_pk_mul_f32 v[50:51], v[50:51], v[50:51]
	v_cvt_pk_bf16_f32 v60, v60, v61
	v_cvt_pk_bf16_f32 v61, v62, v63
	v_cvt_pk_bf16_f32 v62, v56, v57
	v_cvt_pk_bf16_f32 v63, v58, v59
	v_cvt_pk_bf16_f32 v52, v52, v53
	v_cvt_pk_bf16_f32 v53, v54, v55
	v_cvt_pk_bf16_f32 v54, v48, v49
	v_cvt_pk_bf16_f32 v55, v50, v51
	s_add_u32 s98, s68, 0x100000
	s_addc_u32 s99, s69, 0
	global_store_dwordx4 v249, v[60:63], s[98:99]
	global_store_dwordx4 v249, v[52:55], s[98:99] offset:256
	v_pk_mul_f32 v[44:45], v[44:45], v[250:251] op_sel_hi:[1,0]
	v_pk_mul_f32 v[46:47], v[46:47], v[250:251] op_sel_hi:[1,0]
	v_pk_mul_f32 v[40:41], v[40:41], v[250:251] op_sel_hi:[1,0]
	v_pk_mul_f32 v[42:43], v[42:43], v[250:251] op_sel_hi:[1,0]
	v_pk_mul_f32 v[36:37], v[36:37], v[250:251] op_sel_hi:[1,0]
	v_pk_mul_f32 v[38:39], v[38:39], v[250:251] op_sel_hi:[1,0]
	v_pk_mul_f32 v[32:33], v[32:33], v[250:251] op_sel_hi:[1,0]
	v_pk_mul_f32 v[34:35], v[34:35], v[250:251] op_sel_hi:[1,0]
	v_max_f32_e32 v44, 0, v44
	v_max_f32_e32 v45, 0, v45
	v_max_f32_e32 v46, 0, v46
	v_max_f32_e32 v47, 0, v47
	v_max_f32_e32 v40, 0, v40
	v_max_f32_e32 v41, 0, v41
	v_max_f32_e32 v42, 0, v42
	v_max_f32_e32 v43, 0, v43
	v_max_f32_e32 v36, 0, v36
	v_max_f32_e32 v37, 0, v37
	v_max_f32_e32 v38, 0, v38
	v_max_f32_e32 v39, 0, v39
	v_max_f32_e32 v32, 0, v32
	v_max_f32_e32 v33, 0, v33
	v_max_f32_e32 v34, 0, v34
	v_max_f32_e32 v35, 0, v35
	v_pk_mul_f32 v[44:45], v[44:45], v[44:45]
	v_pk_mul_f32 v[46:47], v[46:47], v[46:47]
	v_pk_mul_f32 v[40:41], v[40:41], v[40:41]
	v_pk_mul_f32 v[42:43], v[42:43], v[42:43]
	v_pk_mul_f32 v[36:37], v[36:37], v[36:37]
	v_pk_mul_f32 v[38:39], v[38:39], v[38:39]
	v_pk_mul_f32 v[32:33], v[32:33], v[32:33]
	v_pk_mul_f32 v[34:35], v[34:35], v[34:35]
	v_cvt_pk_bf16_f32 v44, v44, v45
	v_cvt_pk_bf16_f32 v45, v46, v47
	v_cvt_pk_bf16_f32 v46, v40, v41
	v_cvt_pk_bf16_f32 v47, v42, v43
	v_cvt_pk_bf16_f32 v36, v36, v37
	v_cvt_pk_bf16_f32 v37, v38, v39
	v_cvt_pk_bf16_f32 v38, v32, v33
	v_cvt_pk_bf16_f32 v39, v34, v35
	s_add_u32 s98, s68, 0x120000
	s_addc_u32 s99, s69, 0
	global_store_dwordx4 v249, v[44:47], s[98:99]
	global_store_dwordx4 v249, v[36:39], s[98:99] offset:256
	v_pk_mul_f32 v[28:29], v[28:29], v[252:253] op_sel_hi:[1,0]
	v_pk_mul_f32 v[30:31], v[30:31], v[252:253] op_sel_hi:[1,0]
	v_pk_mul_f32 v[24:25], v[24:25], v[252:253] op_sel_hi:[1,0]
	v_pk_mul_f32 v[26:27], v[26:27], v[252:253] op_sel_hi:[1,0]
	v_pk_mul_f32 v[20:21], v[20:21], v[252:253] op_sel_hi:[1,0]
	v_pk_mul_f32 v[22:23], v[22:23], v[252:253] op_sel_hi:[1,0]
	v_pk_mul_f32 v[16:17], v[16:17], v[252:253] op_sel_hi:[1,0]
	v_pk_mul_f32 v[18:19], v[18:19], v[252:253] op_sel_hi:[1,0]
	v_max_f32_e32 v28, 0, v28
	v_max_f32_e32 v29, 0, v29
	v_max_f32_e32 v30, 0, v30
	v_max_f32_e32 v31, 0, v31
	v_max_f32_e32 v24, 0, v24
	v_max_f32_e32 v25, 0, v25
	v_max_f32_e32 v26, 0, v26
	v_max_f32_e32 v27, 0, v27
	v_max_f32_e32 v20, 0, v20
	v_max_f32_e32 v21, 0, v21
	v_max_f32_e32 v22, 0, v22
	v_max_f32_e32 v23, 0, v23
	v_max_f32_e32 v16, 0, v16
	v_max_f32_e32 v17, 0, v17
	v_max_f32_e32 v18, 0, v18
	v_max_f32_e32 v19, 0, v19
	v_pk_mul_f32 v[28:29], v[28:29], v[28:29]
	v_pk_mul_f32 v[30:31], v[30:31], v[30:31]
	v_pk_mul_f32 v[24:25], v[24:25], v[24:25]
	v_pk_mul_f32 v[26:27], v[26:27], v[26:27]
	v_pk_mul_f32 v[20:21], v[20:21], v[20:21]
	v_pk_mul_f32 v[22:23], v[22:23], v[22:23]
	v_pk_mul_f32 v[16:17], v[16:17], v[16:17]
	v_pk_mul_f32 v[18:19], v[18:19], v[18:19]
	v_cvt_pk_bf16_f32 v28, v28, v29
	v_cvt_pk_bf16_f32 v29, v30, v31
	v_cvt_pk_bf16_f32 v30, v24, v25
	v_cvt_pk_bf16_f32 v31, v26, v27
	v_cvt_pk_bf16_f32 v20, v20, v21
	v_cvt_pk_bf16_f32 v21, v22, v23
	v_cvt_pk_bf16_f32 v22, v16, v17
	v_cvt_pk_bf16_f32 v23, v18, v19
	s_add_u32 s98, s68, 0x140000
	s_addc_u32 s99, s69, 0
	global_store_dwordx4 v249, v[28:31], s[98:99]
	global_store_dwordx4 v249, v[20:23], s[98:99] offset:256
	v_pk_mul_f32 v[12:13], v[12:13], v[254:255] op_sel_hi:[1,0]
	v_pk_mul_f32 v[14:15], v[14:15], v[254:255] op_sel_hi:[1,0]
	v_pk_mul_f32 v[8:9], v[8:9], v[254:255] op_sel_hi:[1,0]
	v_pk_mul_f32 v[10:11], v[10:11], v[254:255] op_sel_hi:[1,0]
	v_pk_mul_f32 v[4:5], v[4:5], v[254:255] op_sel_hi:[1,0]
	v_pk_mul_f32 v[6:7], v[6:7], v[254:255] op_sel_hi:[1,0]
	v_pk_mul_f32 v[0:1], v[0:1], v[254:255] op_sel_hi:[1,0]
	v_pk_mul_f32 v[2:3], v[2:3], v[254:255] op_sel_hi:[1,0]
	v_max_f32_e32 v12, 0, v12
	v_max_f32_e32 v13, 0, v13
	v_max_f32_e32 v14, 0, v14
	v_max_f32_e32 v15, 0, v15
	v_max_f32_e32 v8, 0, v8
	v_max_f32_e32 v9, 0, v9
	v_max_f32_e32 v10, 0, v10
	v_max_f32_e32 v11, 0, v11
	v_max_f32_e32 v4, 0, v4
	v_max_f32_e32 v5, 0, v5
	v_max_f32_e32 v6, 0, v6
	v_max_f32_e32 v7, 0, v7
	v_max_f32_e32 v0, 0, v0
	v_max_f32_e32 v1, 0, v1
	v_max_f32_e32 v2, 0, v2
	v_max_f32_e32 v3, 0, v3
	v_pk_mul_f32 v[12:13], v[12:13], v[12:13]
	v_pk_mul_f32 v[14:15], v[14:15], v[14:15]
	v_pk_mul_f32 v[8:9], v[8:9], v[8:9]
	v_pk_mul_f32 v[10:11], v[10:11], v[10:11]
	v_pk_mul_f32 v[4:5], v[4:5], v[4:5]
	v_pk_mul_f32 v[6:7], v[6:7], v[6:7]
	v_pk_mul_f32 v[0:1], v[0:1], v[0:1]
	v_pk_mul_f32 v[2:3], v[2:3], v[2:3]
	v_cvt_pk_bf16_f32 v12, v12, v13
	v_cvt_pk_bf16_f32 v13, v14, v15
	v_cvt_pk_bf16_f32 v14, v8, v9
	v_cvt_pk_bf16_f32 v15, v10, v11
	v_cvt_pk_bf16_f32 v4, v4, v5
	v_cvt_pk_bf16_f32 v5, v6, v7
	v_cvt_pk_bf16_f32 v6, v0, v1
	v_cvt_pk_bf16_f32 v7, v2, v3
	s_add_u32 s98, s68, 0x160000
	s_addc_u32 s99, s69, 0
	global_store_dwordx4 v249, v[12:15], s[98:99]
	global_store_dwordx4 v249, v[4:7], s[98:99] offset:256
	s_cbranch_vccnz .LBB0_1484
	s_andn2_b64 vcc, exec, s[2:3]
	s_cbranch_vccnz .LBB0_1483
	s_barrier
	s_branch .LBB0_1483
